# v10 + HGRN2 sample-token unit: loads of tokens 2 and 3 issued with tokens 0/1 on fresh registers; gate row loaded before the state stores
# baseline (speedup 1.0000x reference)
; #define LAS __attribute__((address_space(3)))
; __device__ __forceinline__ float ex2(float x) { return __builtin_amdgcn_exp2f(x); }
; __device__ __forceinline__ void hgrn_sample_unit(int unit, LAS unsigned char* lds, const float* sh, const float* HLF, const bf16* HQ, const bf16* HV, const bf16* HG, bf16* MIX, float* ohs, gu32* rdy4) {
;     const int tid = threadIdx.x, wid = tid >> 6, b = unit >> 2, h = unit & 3, v4 = tid & 31, kq = tid >> 5;
;     LAS float* OP = (LAS float*)lds;
;     LAS float* PS = (LAS float*)(lds + 32768);
;     const float* s0 = sh + ((size_t)unit * 128 + 8 * kq) * 128 + 4 * v4;
;     f32x4 S[8];
; #pragma unroll
;     for (int i = 0; i < 8; ++i) S[i] = *(const f32x4*)(s0 + i * 128);
; #pragma unroll
;     for (int t = 0; t < 4; ++t) {
;         const size_t rb = (size_t)(MP + 4 * b + t) * 512 + h * 128;
;         const v2u vw = *(const v2u*)(HV + rb + 4 * v4);
;         const f32x4 vv = {__builtin_bit_cast(float, vw.x << 16), __builtin_bit_cast(float, vw.x & 0xffff0000u), __builtin_bit_cast(float, vw.y << 16), __builtin_bit_cast(float, vw.y & 0xffff0000u)};
;         f32x4 po = {0.f, 0.f, 0.f, 0.f};
; #pragma unroll
;         for (int i = 0; i < 8; ++i) { const float f = ex2(HLF[rb + 8 * kq + i] * LOG2E_F), q = bf2f(HQ[rb + 8 * kq + i]); S[i] = S[i] * f + vv * (1.0f - f); po += S[i] * q; }
.LBB0_602:
	s_and_b32 s22, s26, -4
	s_ashr_i32 s23, s22, 31
	s_and_b32 s12, s0, 0x180
	s_lshl_b64 s[24:25], s[22:23], 9
	s_or_b32 s23, s24, s12
	s_add_u32 s28, s23, 0x800000
	s_addc_u32 s29, s25, 0
	v_lshl_add_u64 v[2:3], s[28:29], 1, v[26:27]
	global_load_dwordx2 v[48:49], v[2:3], off
	v_mov_b32_e32 v3, s29
	v_or_b32_e32 v2, s28, v22
	v_lshl_add_u64 v[4:5], v[2:3], 2, s[14:15]
	global_load_dwordx4 v[10:13], v[4:5], off
	v_lshl_add_u64 v[2:3], v[2:3], 1, s[16:17]
	global_load_dwordx4 v[14:17], v[2:3], off
	global_load_dwordx4 v[52:55], v[4:5], off offset:16
	v_lshl_add_u64 v[2:3], v[30:31], 0, v[28:29]
	global_load_dwordx4 v[56:59], v[2:3], off
	global_load_dwordx4 v[60:63], v[2:3], off offset:512
	global_load_dwordx4 v[68:71], v[2:3], off offset:1024
	global_load_dwordx4 v[72:75], v[2:3], off offset:1536
	global_load_dwordx4 v[76:79], v[2:3], off offset:2048
	global_load_dwordx4 v[80:83], v[2:3], off offset:2560
	global_load_dwordx4 v[84:87], v[2:3], off offset:3072
	global_load_dwordx4 v[88:91], v[2:3], off offset:3584
	s_add_u32 s28, s23, 0x800200
	s_addc_u32 s29, s25, 0
	v_or_b32_e32 v2, s28, v22
	v_lshl_add_u64 v[64:65], s[28:29], 1, v[26:27]
	v_mov_b32_e32 v3, s29
	v_lshl_add_u64 v[92:93], v[2:3], 2, s[14:15]
	v_lshl_add_u64 v[94:95], v[2:3], 1, s[16:17]
	global_load_dwordx2 v[96:97], v[64:65], off
	global_load_dwordx4 v[18:21], v[92:93], off
	global_load_dwordx4 v[6:9], v[92:93], off offset:16
	global_load_dwordx4 v[2:5], v[94:95], off
	s_add_u32 s28, s23, 0x800400
	s_addc_u32 s29, s25, 0
	s_add_u32 s24, s23, 0x800600
	s_addc_u32 s25, s25, 0
	v_lshl_add_u64 v[216:217], s[28:29], 1, v[26:27]
	global_load_dwordx2 v[200:201], v[216:217], off
	v_mov_b32_e32 v219, s29
	v_or_b32_e32 v218, s28, v22
	v_lshl_add_u64 v[220:221], v[218:219], 2, s[14:15]
	v_lshl_add_u64 v[222:223], v[218:219], 1, s[16:17]
	global_load_dwordx4 v[204:207], v[220:221], off
	global_load_dwordx4 v[208:211], v[220:221], off offset:16
	global_load_dwordx4 v[212:215], v[222:223], off
	v_lshl_add_u64 v[216:217], s[24:25], 1, v[26:27]
	global_load_dwordx2 v[224:225], v[216:217], off
	v_mov_b32_e32 v219, s25
	v_or_b32_e32 v218, s24, v22
	v_lshl_add_u64 v[220:221], v[218:219], 2, s[14:15]
	v_lshl_add_u64 v[222:223], v[218:219], 1, s[16:17]
	global_load_dwordx4 v[232:235], v[220:221], off
	global_load_dwordx4 v[236:239], v[220:221], off offset:16
	global_load_dwordx4 v[240:243], v[222:223], off
	v_cmp_lt_i32_e32 vcc, v39, v38
	s_waitcnt vmcnt(23)
	v_lshlrev_b32_e32 v64, 16, v48
	v_and_b32_e32 v65, 0xffff0000, v48
	v_lshlrev_b32_e32 v48, 16, v49
	v_and_b32_e32 v49, 0xffff0000, v49
	s_waitcnt vmcnt(22)
	v_mul_f32_e32 v51, 0x3fb8aa3b, v10
	v_mul_f32_e32 v11, 0x3fb8aa3b, v11
	s_waitcnt vmcnt(20)
	v_mul_f32_e32 v93, 0x3fb8aa3b, v54
	v_exp_f32_e32 v54, v51
	v_mul_f32_e32 v67, 0x3fb8aa3b, v12
	v_exp_f32_e32 v94, v11
	v_mul_f32_e32 v13, 0x3fb8aa3b, v13
	v_exp_f32_e32 v98, v67
	v_lshlrev_b32_e32 v12, 16, v15
	v_and_b32_e32 v92, 0xffff0000, v15
	v_mul_f32_e32 v15, 0x3fb8aa3b, v52
	v_exp_f32_e32 v100, v13
	v_mul_f32_e32 v53, 0x3fb8aa3b, v53
	v_exp_f32_e32 v102, v15
	v_sub_f32_e32 v108, 1.0, v54
	v_exp_f32_e32 v104, v53
	v_sub_f32_e32 v110, 1.0, v94
	v_pk_mul_f32 v[120:121], v[108:109], v[64:65] op_sel_hi:[0,1]
	v_pk_mul_f32 v[108:109], v[108:109], v[48:49] op_sel_hi:[0,1]
	v_lshlrev_b32_e32 v10, 16, v14
	v_sub_f32_e32 v112, 1.0, v98
	v_pk_mul_f32 v[122:123], v[110:111], v[48:49] op_sel_hi:[0,1]
	v_pk_mul_f32 v[110:111], v[110:111], v[64:65] op_sel_hi:[0,1]
	s_waitcnt vmcnt(19)
	v_pk_fma_f32 v[58:59], v[58:59], v[54:55], v[108:109] op_sel_hi:[1,0,1]
	v_pk_fma_f32 v[56:57], v[56:57], v[54:55], v[120:121] op_sel_hi:[1,0,1]
	v_and_b32_e32 v14, 0xffff0000, v14
	v_sub_f32_e32 v114, 1.0, v100
	v_pk_mul_f32 v[124:125], v[112:113], v[64:65] op_sel_hi:[0,1]
	v_pk_mul_f32 v[112:113], v[112:113], v[48:49] op_sel_hi:[0,1]
	s_waitcnt vmcnt(18)
	v_pk_fma_f32 v[60:61], v[60:61], v[94:95], v[110:111] op_sel_hi:[1,0,1]
	v_pk_fma_f32 v[62:63], v[62:63], v[94:95], v[122:123] op_sel_hi:[1,0,1]
	v_pk_fma_f32 v[94:95], v[10:11], v[56:57], 0 op_sel_hi:[0,1,0]
	v_pk_fma_f32 v[10:11], v[10:11], v[58:59], 0 op_sel_hi:[0,1,0]
	v_exp_f32_e32 v106, v93
	v_sub_f32_e32 v116, 1.0, v102
	v_pk_mul_f32 v[126:127], v[114:115], v[48:49] op_sel_hi:[0,1]
	v_pk_mul_f32 v[114:115], v[114:115], v[64:65] op_sel_hi:[0,1]
	s_waitcnt vmcnt(17)
	v_pk_fma_f32 v[70:71], v[70:71], v[98:99], v[112:113] op_sel_hi:[1,0,1]
	v_pk_fma_f32 v[68:69], v[68:69], v[98:99], v[124:125] op_sel_hi:[1,0,1]
	v_pk_fma_f32 v[10:11], v[14:15], v[62:63], v[10:11] op_sel_hi:[0,1,1]
	v_pk_fma_f32 v[14:15], v[14:15], v[60:61], v[94:95] op_sel_hi:[0,1,1]
	v_sub_f32_e32 v118, 1.0, v104
	v_pk_mul_f32 v[128:129], v[116:117], v[64:65] op_sel_hi:[0,1]
	v_pk_mul_f32 v[116:117], v[116:117], v[48:49] op_sel_hi:[0,1]
	s_waitcnt vmcnt(16)
	v_pk_fma_f32 v[72:73], v[72:73], v[100:101], v[114:115] op_sel_hi:[1,0,1]
	v_pk_fma_f32 v[74:75], v[74:75], v[100:101], v[126:127] op_sel_hi:[1,0,1]
	v_pk_fma_f32 v[14:15], v[12:13], v[68:69], v[14:15] op_sel_hi:[0,1,1]
	v_pk_fma_f32 v[10:11], v[12:13], v[70:71], v[10:11] op_sel_hi:[0,1,1]
	v_lshlrev_b32_e32 v52, 16, v16
	v_pk_mul_f32 v[130:131], v[118:119], v[48:49] op_sel_hi:[0,1]
	v_pk_mul_f32 v[118:119], v[118:119], v[64:65] op_sel_hi:[0,1]
	s_waitcnt vmcnt(15)
	v_pk_fma_f32 v[78:79], v[78:79], v[102:103], v[116:117] op_sel_hi:[1,0,1]
	v_pk_fma_f32 v[76:77], v[76:77], v[102:103], v[128:129] op_sel_hi:[1,0,1]
	v_pk_fma_f32 v[10:11], v[92:93], v[74:75], v[10:11] op_sel_hi:[0,1,1]
	v_pk_fma_f32 v[12:13], v[92:93], v[72:73], v[14:15] op_sel_hi:[0,1,1]
	v_and_b32_e32 v16, 0xffff0000, v16
	s_waitcnt vmcnt(14)
; #define LAS __attribute__((address_space(3)))
; __device__ __forceinline__ float ex2(float x) { return __builtin_amdgcn_exp2f(x); }
; __device__ __forceinline__ void hgrn_sample_unit(int unit, LAS unsigned char* lds, const float* sh, const float* HLF, const bf16* HQ, const bf16* HV, const bf16* HG, bf16* MIX, float* ohs, gu32* rdy4) {
;     ...
;     for (int t = 0; t < 4; ++t) {
;         const size_t rb = (size_t)(MP + 4 * b + t) * 512 + h * 128;
;         const v2u vw = *(const v2u*)(HV + rb + 4 * v4);
;         const f32x4 vv = {__builtin_bit_cast(float, vw.x << 16), __builtin_bit_cast(float, vw.x & 0xffff0000u), __builtin_bit_cast(float, vw.y << 16), __builtin_bit_cast(float, vw.y & 0xffff0000u)};
;         f32x4 po = {0.f, 0.f, 0.f, 0.f};
; #pragma unroll
;         for (int i = 0; i < 8; ++i) { const float f = ex2(HLF[rb + 8 * kq + i] * LOG2E_F), q = bf2f(HQ[rb + 8 * kq + i]); S[i] = S[i] * f + vv * (1.0f - f); po += S[i] * q; }
;         *(LAS f32x4*)(OP + (t * 16 + kq) * 128 + 4 * v4) = po;
	v_pk_fma_f32 v[80:81], v[80:81], v[104:105], v[118:119] op_sel_hi:[1,0,1]
	v_pk_fma_f32 v[82:83], v[82:83], v[104:105], v[130:131] op_sel_hi:[1,0,1]
	v_pk_fma_f32 v[12:13], v[52:53], v[76:77], v[12:13] op_sel_hi:[0,1,1]
	v_pk_fma_f32 v[10:11], v[52:53], v[78:79], v[10:11] op_sel_hi:[0,1,1]
	v_pk_fma_f32 v[10:11], v[16:17], v[82:83], v[10:11] op_sel_hi:[0,1,1]
	v_pk_fma_f32 v[12:13], v[16:17], v[80:81], v[12:13] op_sel_hi:[0,1,1]
	v_sub_f32_e32 v16, 1.0, v106
	v_mul_f32_e32 v15, 0x3fb8aa3b, v55
	v_pk_mul_f32 v[52:53], v[16:17], v[64:65] op_sel_hi:[0,1]
	v_pk_mul_f32 v[92:93], v[16:17], v[48:49] op_sel_hi:[0,1]
	v_exp_f32_e32 v16, v15
	v_lshlrev_b32_e32 v14, 16, v17
	s_waitcnt vmcnt(13)
	v_pk_fma_f32 v[84:85], v[84:85], v[106:107], v[52:53] op_sel_hi:[1,0,1]
	v_pk_fma_f32 v[86:87], v[86:87], v[106:107], v[92:93] op_sel_hi:[1,0,1]
	v_pk_fma_f32 v[52:53], v[14:15], v[84:85], v[12:13] op_sel_hi:[0,1,1]
	v_sub_f32_e32 v12, 1.0, v16
	v_pk_mul_f32 v[48:49], v[12:13], v[48:49] op_sel_hi:[0,1]
	v_pk_mul_f32 v[12:13], v[12:13], v[64:65] op_sel_hi:[0,1]
	v_pk_fma_f32 v[10:11], v[14:15], v[86:87], v[10:11] op_sel_hi:[0,1,1]
	v_and_b32_e32 v14, 0xffff0000, v17
	s_waitcnt vmcnt(12)
	v_pk_fma_f32 v[64:65], v[88:89], v[16:17], v[12:13] op_sel_hi:[1,0,1]
	v_pk_fma_f32 v[48:49], v[90:91], v[16:17], v[48:49] op_sel_hi:[1,0,1]
	s_waitcnt vmcnt(11)
	v_lshlrev_b32_e32 v88, 16, v96
	v_pk_fma_f32 v[12:13], v[14:15], v[48:49], v[10:11] op_sel_hi:[0,1,1]
	v_pk_fma_f32 v[10:11], v[14:15], v[64:65], v[52:53] op_sel_hi:[0,1,1]
	ds_write_b128 v1, v[10:13]
	s_waitcnt vmcnt(10)
	v_mul_f32_e32 v10, 0x3fb8aa3b, v18
	v_exp_f32_e32 v10, v10
	v_and_b32_e32 v89, 0xffff0000, v96
	v_lshlrev_b32_e32 v90, 16, v97
	v_and_b32_e32 v91, 0xffff0000, v97
	v_sub_f32_e32 v12, 1.0, v10
	v_pk_mul_f32 v[14:15], v[12:13], v[88:89] op_sel_hi:[0,1]
	v_pk_mul_f32 v[12:13], v[12:13], v[90:91] op_sel_hi:[0,1]
	v_pk_fma_f32 v[58:59], v[58:59], v[10:11], v[12:13] op_sel_hi:[1,0,1]
	v_mul_f32_e32 v19, 0x3fb8aa3b, v19
	v_pk_fma_f32 v[56:57], v[56:57], v[10:11], v[14:15] op_sel_hi:[1,0,1]
	v_exp_f32_e32 v94, v19
	v_mul_f32_e32 v20, 0x3fb8aa3b, v20
	v_exp_f32_e32 v20, v20
	s_waitcnt vmcnt(8)
	v_lshlrev_b32_e32 v18, 16, v2
	v_sub_f32_e32 v98, 1.0, v94
	v_pk_mul_f32 v[100:101], v[98:99], v[90:91] op_sel_hi:[0,1]
	v_pk_mul_f32 v[98:99], v[98:99], v[88:89] op_sel_hi:[0,1]
	v_pk_fma_f32 v[96:97], v[18:19], v[56:57], 0 op_sel_hi:[0,1,0]
	v_and_b32_e32 v2, 0xffff0000, v2
	v_pk_fma_f32 v[60:61], v[60:61], v[94:95], v[98:99] op_sel_hi:[1,0,1]
	v_pk_fma_f32 v[62:63], v[62:63], v[94:95], v[100:101] op_sel_hi:[1,0,1]
	v_pk_fma_f32 v[94:95], v[2:3], v[60:61], v[96:97] op_sel_hi:[0,1,1]
	v_sub_f32_e32 v96, 1.0, v20
	v_pk_mul_f32 v[98:99], v[96:97], v[88:89] op_sel_hi:[0,1]
	v_pk_mul_f32 v[96:97], v[96:97], v[90:91] op_sel_hi:[0,1]
	v_pk_fma_f32 v[70:71], v[70:71], v[20:21], v[96:97] op_sel_hi:[1,0,1]
	v_pk_fma_f32 v[68:69], v[68:69], v[20:21], v[98:99] op_sel_hi:[1,0,1]
	v_mul_f32_e32 v20, 0x3fb8aa3b, v21
	v_pk_fma_f32 v[18:19], v[18:19], v[58:59], 0 op_sel_hi:[0,1,0]
	v_exp_f32_e32 v20, v20
	v_pk_fma_f32 v[18:19], v[2:3], v[62:63], v[18:19] op_sel_hi:[0,1,1]
	v_lshlrev_b32_e32 v2, 16, v3
	v_pk_fma_f32 v[94:95], v[2:3], v[68:69], v[94:95] op_sel_hi:[0,1,1]
	v_pk_fma_f32 v[18:19], v[2:3], v[70:71], v[18:19] op_sel_hi:[0,1,1]
	v_and_b32_e32 v2, 0xffff0000, v3
	v_mul_f32_e32 v3, 0x3fb8aa3b, v6
	v_exp_f32_e32 v6, v3
	v_sub_f32_e32 v96, 1.0, v20
	v_pk_mul_f32 v[98:99], v[96:97], v[90:91] op_sel_hi:[0,1]
	v_pk_mul_f32 v[96:97], v[96:97], v[88:89] op_sel_hi:[0,1]
	v_pk_fma_f32 v[72:73], v[72:73], v[20:21], v[96:97] op_sel_hi:[1,0,1]
	v_pk_fma_f32 v[74:75], v[74:75], v[20:21], v[98:99] op_sel_hi:[1,0,1]
	v_lshlrev_b32_e32 v20, 16, v4
	v_pk_fma_f32 v[18:19], v[2:3], v[74:75], v[18:19] op_sel_hi:[0,1,1]
	v_pk_fma_f32 v[2:3], v[2:3], v[72:73], v[94:95] op_sel_hi:[0,1,1]
	v_sub_f32_e32 v94, 1.0, v6
	v_pk_mul_f32 v[96:97], v[94:95], v[88:89] op_sel_hi:[0,1]
	v_pk_mul_f32 v[94:95], v[94:95], v[90:91] op_sel_hi:[0,1]
	v_pk_fma_f32 v[78:79], v[78:79], v[6:7], v[94:95] op_sel_hi:[1,0,1]
	v_pk_fma_f32 v[76:77], v[76:77], v[6:7], v[96:97] op_sel_hi:[1,0,1]
	v_mul_f32_e32 v6, 0x3fb8aa3b, v7
	v_exp_f32_e32 v6, v6
	v_pk_fma_f32 v[2:3], v[20:21], v[76:77], v[2:3] op_sel_hi:[0,1,1]
	v_pk_fma_f32 v[18:19], v[20:21], v[78:79], v[18:19] op_sel_hi:[0,1,1]
	v_and_b32_e32 v4, 0xffff0000, v4
	v_sub_f32_e32 v20, 1.0, v6
	v_pk_mul_f32 v[94:95], v[20:21], v[90:91] op_sel_hi:[0,1]
	v_pk_mul_f32 v[20:21], v[20:21], v[88:89] op_sel_hi:[0,1]
	v_pk_fma_f32 v[80:81], v[80:81], v[6:7], v[20:21] op_sel_hi:[1,0,1]
	v_pk_fma_f32 v[82:83], v[82:83], v[6:7], v[94:95] op_sel_hi:[1,0,1]
	v_mul_f32_e32 v6, 0x3fb8aa3b, v8
	v_exp_f32_e32 v6, v6
	v_pk_fma_f32 v[18:19], v[4:5], v[82:83], v[18:19] op_sel_hi:[0,1,1]
	v_pk_fma_f32 v[2:3], v[4:5], v[80:81], v[2:3] op_sel_hi:[0,1,1]
	v_lshlrev_b32_e32 v4, 16, v5
	v_sub_f32_e32 v8, 1.0, v6
	v_pk_mul_f32 v[20:21], v[8:9], v[88:89] op_sel_hi:[0,1]
	v_pk_mul_f32 v[94:95], v[8:9], v[90:91] op_sel_hi:[0,1]
	v_pk_fma_f32 v[86:87], v[86:87], v[6:7], v[94:95] op_sel_hi:[1,0,1]
	v_pk_fma_f32 v[84:85], v[84:85], v[6:7], v[20:21] op_sel_hi:[1,0,1]
	v_mul_f32_e32 v6, 0x3fb8aa3b, v9
	v_exp_f32_e32 v6, v6
	v_pk_fma_f32 v[2:3], v[4:5], v[84:85], v[2:3] op_sel_hi:[0,1,1]
	v_pk_fma_f32 v[8:9], v[4:5], v[86:87], v[18:19] op_sel_hi:[0,1,1]
	v_and_b32_e32 v18, 0xffff0000, v5
	v_sub_f32_e32 v4, 1.0, v6
	v_pk_mul_f32 v[20:21], v[4:5], v[90:91] op_sel_hi:[0,1]
	v_pk_mul_f32 v[4:5], v[4:5], v[88:89] op_sel_hi:[0,1]
	v_pk_fma_f32 v[64:65], v[64:65], v[6:7], v[4:5] op_sel_hi:[1,0,1]
	v_pk_fma_f32 v[48:49], v[48:49], v[6:7], v[20:21] op_sel_hi:[1,0,1]
	v_pk_fma_f32 v[2:3], v[18:19], v[64:65], v[2:3] op_sel_hi:[0,1,1]
	v_pk_fma_f32 v[4:5], v[18:19], v[48:49], v[8:9] op_sel_hi:[0,1,1]
	ds_write_b128 v1, v[2:5] offset:8192
	s_waitcnt vmcnt(7)
; #define LAS __attribute__((address_space(3)))
; __device__ __forceinline__ float ex2(float x) { return __builtin_amdgcn_exp2f(x); }
; __device__ __forceinline__ void hgrn_sample_unit(int unit, LAS unsigned char* lds, const float* sh, const float* HLF, const bf16* HQ, const bf16* HV, const bf16* HG, bf16* MIX, float* ohs, gu32* rdy4) {
;     ...
;     for (int t = 0; t < 4; ++t) {
;         const size_t rb = (size_t)(MP + 4 * b + t) * 512 + h * 128;
;         const v2u vw = *(const v2u*)(HV + rb + 4 * v4);
;         const f32x4 vv = {__builtin_bit_cast(float, vw.x << 16), __builtin_bit_cast(float, vw.x & 0xffff0000u), __builtin_bit_cast(float, vw.y << 16), __builtin_bit_cast(float, vw.y & 0xffff0000u)};
;         f32x4 po = {0.f, 0.f, 0.f, 0.f};
; #pragma unroll
;         for (int i = 0; i < 8; ++i) { const float f = ex2(HLF[rb + 8 * kq + i] * LOG2E_F), q = bf2f(HQ[rb + 8 * kq + i]); S[i] = S[i] * f + vv * (1.0f - f); po += S[i] * q; }
;         *(LAS f32x4*)(OP + (t * 16 + kq) * 128 + 4 * v4) = po;
	v_lshlrev_b32_e32 v88, 16, v200
	v_and_b32_e32 v89, 0xffff0000, v200
	s_waitcnt vmcnt(6)
	v_mul_f32_e32 v2, 0x3fb8aa3b, v204
	v_exp_f32_e32 v6, v2
	v_lshlrev_b32_e32 v90, 16, v201
	v_and_b32_e32 v91, 0xffff0000, v201
	v_sub_f32_e32 v2, 1.0, v6
	v_pk_mul_f32 v[8:9], v[2:3], v[88:89] op_sel_hi:[0,1]
	v_pk_mul_f32 v[2:3], v[2:3], v[90:91] op_sel_hi:[0,1]
	v_pk_fma_f32 v[58:59], v[58:59], v[6:7], v[2:3] op_sel_hi:[1,0,1]
	v_pk_fma_f32 v[56:57], v[56:57], v[6:7], v[8:9] op_sel_hi:[1,0,1]
	v_mul_f32_e32 v51, 0x3fb8aa3b, v205
	v_exp_f32_e32 v94, v51
	v_mul_f32_e32 v51, 0x3fb8aa3b, v206
	v_exp_f32_e32 v54, v51
	s_waitcnt vmcnt(4)
	v_lshlrev_b32_e32 v52, 16, v212
	v_sub_f32_e32 v98, 1.0, v94
	v_pk_mul_f32 v[100:101], v[98:99], v[90:91] op_sel_hi:[0,1]
	v_pk_mul_f32 v[98:99], v[98:99], v[88:89] op_sel_hi:[0,1]
	v_pk_fma_f32 v[96:97], v[52:53], v[56:57], 0 op_sel_hi:[0,1,0]
	v_and_b32_e32 v10, 0xffff0000, v212
	v_pk_fma_f32 v[60:61], v[60:61], v[94:95], v[98:99] op_sel_hi:[1,0,1]
	v_pk_fma_f32 v[62:63], v[62:63], v[94:95], v[100:101] op_sel_hi:[1,0,1]
	v_pk_fma_f32 v[94:95], v[10:11], v[60:61], v[96:97] op_sel_hi:[0,1,1]
	v_sub_f32_e32 v96, 1.0, v54
	v_pk_mul_f32 v[98:99], v[96:97], v[88:89] op_sel_hi:[0,1]
	v_pk_mul_f32 v[96:97], v[96:97], v[90:91] op_sel_hi:[0,1]
	v_mul_f32_e32 v51, 0x3fb8aa3b, v207
	v_pk_fma_f32 v[52:53], v[52:53], v[58:59], 0 op_sel_hi:[0,1,0]
	v_pk_fma_f32 v[70:71], v[70:71], v[54:55], v[96:97] op_sel_hi:[1,0,1]
	v_pk_fma_f32 v[68:69], v[68:69], v[54:55], v[98:99] op_sel_hi:[1,0,1]
	v_exp_f32_e32 v54, v51
	v_pk_fma_f32 v[52:53], v[10:11], v[62:63], v[52:53] op_sel_hi:[0,1,1]
	v_lshlrev_b32_e32 v10, 16, v213
	v_pk_fma_f32 v[94:95], v[10:11], v[68:69], v[94:95] op_sel_hi:[0,1,1]
	v_pk_fma_f32 v[52:53], v[10:11], v[70:71], v[52:53] op_sel_hi:[0,1,1]
	v_and_b32_e32 v10, 0xffff0000, v213
	v_mul_f32_e32 v11, 0x3fb8aa3b, v208
	v_exp_f32_e32 v14, v11
	v_sub_f32_e32 v96, 1.0, v54
	v_pk_mul_f32 v[98:99], v[96:97], v[90:91] op_sel_hi:[0,1]
	v_pk_mul_f32 v[96:97], v[96:97], v[88:89] op_sel_hi:[0,1]
	v_pk_fma_f32 v[72:73], v[72:73], v[54:55], v[96:97] op_sel_hi:[1,0,1]
	v_pk_fma_f32 v[74:75], v[74:75], v[54:55], v[98:99] op_sel_hi:[1,0,1]
	v_lshlrev_b32_e32 v54, 16, v214
	v_pk_fma_f32 v[52:53], v[10:11], v[74:75], v[52:53] op_sel_hi:[0,1,1]
	v_pk_fma_f32 v[10:11], v[10:11], v[72:73], v[94:95] op_sel_hi:[0,1,1]
	v_sub_f32_e32 v94, 1.0, v14
	v_pk_mul_f32 v[96:97], v[94:95], v[88:89] op_sel_hi:[0,1]
	v_pk_mul_f32 v[94:95], v[94:95], v[90:91] op_sel_hi:[0,1]
	v_pk_fma_f32 v[78:79], v[78:79], v[14:15], v[94:95] op_sel_hi:[1,0,1]
	v_pk_fma_f32 v[76:77], v[76:77], v[14:15], v[96:97] op_sel_hi:[1,0,1]
	v_mul_f32_e32 v14, 0x3fb8aa3b, v209
	v_exp_f32_e32 v14, v14
	v_pk_fma_f32 v[10:11], v[54:55], v[76:77], v[10:11] op_sel_hi:[0,1,1]
	v_pk_fma_f32 v[52:53], v[54:55], v[78:79], v[52:53] op_sel_hi:[0,1,1]
	v_and_b32_e32 v12, 0xffff0000, v214
	v_sub_f32_e32 v54, 1.0, v14
	v_pk_mul_f32 v[94:95], v[54:55], v[90:91] op_sel_hi:[0,1]
	v_pk_mul_f32 v[54:55], v[54:55], v[88:89] op_sel_hi:[0,1]
	v_pk_fma_f32 v[80:81], v[80:81], v[14:15], v[54:55] op_sel_hi:[1,0,1]
	v_pk_fma_f32 v[82:83], v[82:83], v[14:15], v[94:95] op_sel_hi:[1,0,1]
	v_mul_f32_e32 v14, 0x3fb8aa3b, v210
	v_exp_f32_e32 v14, v14
	v_pk_fma_f32 v[52:53], v[12:13], v[82:83], v[52:53] op_sel_hi:[0,1,1]
	v_pk_fma_f32 v[10:11], v[12:13], v[80:81], v[10:11] op_sel_hi:[0,1,1]
	v_lshlrev_b32_e32 v12, 16, v215
	v_sub_f32_e32 v16, 1.0, v14
	v_pk_mul_f32 v[54:55], v[16:17], v[88:89] op_sel_hi:[0,1]
	v_pk_mul_f32 v[94:95], v[16:17], v[90:91] op_sel_hi:[0,1]
	v_pk_fma_f32 v[86:87], v[86:87], v[14:15], v[94:95] op_sel_hi:[1,0,1]
	v_pk_fma_f32 v[84:85], v[84:85], v[14:15], v[54:55] op_sel_hi:[1,0,1]
	v_mul_f32_e32 v14, 0x3fb8aa3b, v211
	v_exp_f32_e32 v14, v14
	v_pk_fma_f32 v[10:11], v[12:13], v[84:85], v[10:11] op_sel_hi:[0,1,1]
	v_pk_fma_f32 v[16:17], v[12:13], v[86:87], v[52:53] op_sel_hi:[0,1,1]
	v_and_b32_e32 v52, 0xffff0000, v215
	v_sub_f32_e32 v12, 1.0, v14
	v_pk_mul_f32 v[54:55], v[12:13], v[90:91] op_sel_hi:[0,1]
	v_pk_mul_f32 v[12:13], v[12:13], v[88:89] op_sel_hi:[0,1]
	v_pk_fma_f32 v[64:65], v[64:65], v[14:15], v[12:13] op_sel_hi:[1,0,1]
	v_pk_fma_f32 v[48:49], v[48:49], v[14:15], v[54:55] op_sel_hi:[1,0,1]
	v_pk_fma_f32 v[10:11], v[52:53], v[64:65], v[10:11] op_sel_hi:[0,1,1]
	v_pk_fma_f32 v[12:13], v[52:53], v[48:49], v[16:17] op_sel_hi:[0,1,1]
	ds_write_b128 v1, v[10:13] offset:16384
	s_waitcnt vmcnt(3)
	v_lshlrev_b32_e32 v88, 16, v224
	v_and_b32_e32 v89, 0xffff0000, v224
	s_waitcnt vmcnt(2)
	v_mul_f32_e32 v2, 0x3fb8aa3b, v232
	v_exp_f32_e32 v2, v2
	v_lshlrev_b32_e32 v90, 16, v225
	v_and_b32_e32 v91, 0xffff0000, v225
	s_waitcnt vmcnt(0)
; __device__ __forceinline__ void store2_wt(void* p, unsigned v) { asm volatile("global_store_short %0, %1, off sc1" :: "v"(p), "v"(v) : "memory"); }
; #define LAS __attribute__((address_space(3)))
; __device__ __forceinline__ unsigned f2bf(float f) { unsigned u = __builtin_bit_cast(unsigned, f); return (u + 0x7fffu + ((u >> 16) & 1u)) >> 16; }
; __device__ __forceinline__ float ex2(float x) { return __builtin_amdgcn_exp2f(x); }
; __device__ __forceinline__ void hgrn_sample_unit(int unit, LAS unsigned char* lds, const float* sh, const float* HLF, const bf16* HQ, const bf16* HV, const bf16* HG, bf16* MIX, float* ohs, gu32* rdy4) {
;     ...
;         for (int i = 0; i < 8; ++i) { const float f = ex2(HLF[rb + 8 * kq + i] * LOG2E_F), q = bf2f(HQ[rb + 8 * kq + i]); S[i] = S[i] * f + vv * (1.0f - f); po += S[i] * q; }
;         *(LAS f32x4*)(OP + (t * 16 + kq) * 128 + 4 * v4) = po;
;     }
;     float* so = ohs + ((size_t)unit * 128 + 8 * kq) * 128 + 4 * v4;
; #pragma unroll
;     for (int i = 0; i < 8; ++i) *(f32x4*)(so + i * 128) = S[i];
;     ...
;     pg8::store2_wt(MIX + row * 1024 + 512 + h * 128 + v, (unsigned)f2bf(o * rstd * bf2f(HG[row * 512 + h * 128 + v])));
	v_lshlrev_b32_e32 v14, 16, v240
	v_sub_f32_e32 v10, 1.0, v2
	v_pk_mul_f32 v[16:17], v[10:11], v[88:89] op_sel_hi:[0,1]
	v_pk_mul_f32 v[10:11], v[10:11], v[90:91] op_sel_hi:[0,1]
	v_pk_fma_f32 v[12:13], v[58:59], v[2:3], v[10:11] op_sel_hi:[1,0,1]
	v_pk_fma_f32 v[10:11], v[56:57], v[2:3], v[16:17] op_sel_hi:[1,0,1]
	v_mul_f32_e32 v2, 0x3fb8aa3b, v233
	v_exp_f32_e32 v2, v2
	v_pk_fma_f32 v[52:53], v[14:15], v[10:11], 0 op_sel_hi:[0,1,0]
	v_pk_fma_f32 v[54:55], v[14:15], v[12:13], 0 op_sel_hi:[0,1,0]
	v_and_b32_e32 v18, 0xffff0000, v240
	v_sub_f32_e32 v14, 1.0, v2
	v_pk_mul_f32 v[56:57], v[14:15], v[88:89] op_sel_hi:[0,1]
	v_pk_mul_f32 v[14:15], v[14:15], v[90:91] op_sel_hi:[0,1]
	v_pk_fma_f32 v[16:17], v[62:63], v[2:3], v[14:15] op_sel_hi:[1,0,1]
	v_pk_fma_f32 v[14:15], v[60:61], v[2:3], v[56:57] op_sel_hi:[1,0,1]
	v_mul_f32_e32 v2, 0x3fb8aa3b, v234
	v_exp_f32_e32 v2, v2
	v_pk_fma_f32 v[56:57], v[18:19], v[16:17], v[54:55] op_sel_hi:[0,1,1]
	v_pk_fma_f32 v[58:59], v[18:19], v[14:15], v[52:53] op_sel_hi:[0,1,1]
	v_mul_f32_e32 v6, 0x3fb8aa3b, v236
	v_sub_f32_e32 v18, 1.0, v2
	v_pk_mul_f32 v[52:53], v[18:19], v[88:89] op_sel_hi:[0,1]
	v_pk_mul_f32 v[54:55], v[18:19], v[90:91] op_sel_hi:[0,1]
	v_pk_fma_f32 v[54:55], v[70:71], v[2:3], v[54:55] op_sel_hi:[1,0,1]
	v_pk_fma_f32 v[52:53], v[68:69], v[2:3], v[52:53] op_sel_hi:[1,0,1]
	v_mul_f32_e32 v2, 0x3fb8aa3b, v235
	v_exp_f32_e32 v2, v2
	v_lshlrev_b32_e32 v4, 16, v241
	v_exp_f32_e32 v6, v6
	v_pk_fma_f32 v[58:59], v[4:5], v[52:53], v[58:59] op_sel_hi:[0,1,1]
	v_pk_fma_f32 v[56:57], v[4:5], v[54:55], v[56:57] op_sel_hi:[0,1,1]
	v_sub_f32_e32 v4, 1.0, v2
	v_pk_mul_f32 v[60:61], v[4:5], v[88:89] op_sel_hi:[0,1]
	v_pk_mul_f32 v[4:5], v[4:5], v[90:91] op_sel_hi:[0,1]
	v_and_b32_e32 v18, 0xffff0000, v241
	v_pk_fma_f32 v[4:5], v[74:75], v[2:3], v[4:5] op_sel_hi:[1,0,1]
	v_pk_fma_f32 v[2:3], v[72:73], v[2:3], v[60:61] op_sel_hi:[1,0,1]
	v_pk_fma_f32 v[60:61], v[18:19], v[4:5], v[56:57] op_sel_hi:[0,1,1]
	v_sub_f32_e32 v56, 1.0, v6
	v_pk_mul_f32 v[68:69], v[56:57], v[88:89] op_sel_hi:[0,1]
	v_pk_mul_f32 v[56:57], v[56:57], v[90:91] op_sel_hi:[0,1]
	v_pk_fma_f32 v[18:19], v[18:19], v[2:3], v[58:59] op_sel_hi:[0,1,1]
	v_pk_fma_f32 v[58:59], v[78:79], v[6:7], v[56:57] op_sel_hi:[1,0,1]
	v_pk_fma_f32 v[56:57], v[76:77], v[6:7], v[68:69] op_sel_hi:[1,0,1]
	v_mul_f32_e32 v6, 0x3fb8aa3b, v237
	v_exp_f32_e32 v6, v6
	v_lshlrev_b32_e32 v62, 16, v242
	v_pk_fma_f32 v[68:69], v[62:63], v[58:59], v[60:61] op_sel_hi:[0,1,1]
	v_pk_fma_f32 v[18:19], v[62:63], v[56:57], v[18:19] op_sel_hi:[0,1,1]
	v_sub_f32_e32 v60, 1.0, v6
	v_pk_mul_f32 v[70:71], v[60:61], v[88:89] op_sel_hi:[0,1]
	v_pk_mul_f32 v[60:61], v[60:61], v[90:91] op_sel_hi:[0,1]
	v_pk_fma_f32 v[62:63], v[82:83], v[6:7], v[60:61] op_sel_hi:[1,0,1]
	v_pk_fma_f32 v[60:61], v[80:81], v[6:7], v[70:71] op_sel_hi:[1,0,1]
	v_mul_f32_e32 v6, 0x3fb8aa3b, v238
	v_exp_f32_e32 v6, v6
	v_and_b32_e32 v20, 0xffff0000, v242
	v_pk_fma_f32 v[72:73], v[20:21], v[62:63], v[68:69] op_sel_hi:[0,1,1]
	v_pk_fma_f32 v[18:19], v[20:21], v[60:61], v[18:19] op_sel_hi:[0,1,1]
	v_sub_f32_e32 v20, 1.0, v6
	v_pk_mul_f32 v[68:69], v[20:21], v[88:89] op_sel_hi:[0,1]
	v_pk_mul_f32 v[70:71], v[20:21], v[90:91] op_sel_hi:[0,1]
	v_pk_fma_f32 v[70:71], v[86:87], v[6:7], v[70:71] op_sel_hi:[1,0,1]
	v_pk_fma_f32 v[68:69], v[84:85], v[6:7], v[68:69] op_sel_hi:[1,0,1]
	v_mul_f32_e32 v6, 0x3fb8aa3b, v239
	v_exp_f32_e32 v6, v6
	v_lshlrev_b32_e32 v8, 16, v243
	v_pk_fma_f32 v[18:19], v[8:9], v[68:69], v[18:19] op_sel_hi:[0,1,1]
	v_pk_fma_f32 v[72:73], v[8:9], v[70:71], v[72:73] op_sel_hi:[0,1,1]
	v_sub_f32_e32 v8, 1.0, v6
	v_and_b32_e32 v74, 0xffff0000, v243
	v_pk_mul_f32 v[20:21], v[8:9], v[88:89] op_sel_hi:[0,1]
	v_pk_mul_f32 v[8:9], v[8:9], v[90:91] op_sel_hi:[0,1]
	v_pk_fma_f32 v[8:9], v[48:49], v[6:7], v[8:9] op_sel_hi:[1,0,1]
	v_pk_fma_f32 v[6:7], v[64:65], v[6:7], v[20:21] op_sel_hi:[1,0,1]
	v_pk_fma_f32 v[20:21], v[74:75], v[8:9], v[72:73] op_sel_hi:[0,1,1]
	v_pk_fma_f32 v[18:19], v[74:75], v[6:7], v[18:19] op_sel_hi:[0,1,1]
	ds_write_b128 v1, v[18:21] offset:24576
	v_lshl_add_u64 v[18:19], v[32:33], 0, v[28:29]
	v_add_u32_e32 v248, s22, v35
	v_ashrrev_i32_e32 v249, 31, v248
	s_lshl_b32 s98, s12, 1
	s_mov_b32 s99, s13
	v_lshlrev_b64 v[250:251], 10, v[248:249]
	v_lshl_add_u64 v[250:251], s[18:19], 0, v[250:251]
	v_lshl_add_u64 v[250:251], v[250:251], 0, s[98:99]
	v_lshl_add_u64 v[250:251], v[250:251], 0, v[24:25]
	global_load_ushort v252, v[250:251], off
	global_store_dwordx4 v[18:19], v[10:13], off offset:-2048
	global_store_dwordx4 v[18:19], v[14:17], off offset:-1536
	global_store_dwordx4 v[18:19], v[52:55], off offset:-1024
	global_store_dwordx4 v[18:19], v[2:5], off offset:-512
	global_store_dwordx4 v[18:19], v[56:59], off
	global_store_dwordx4 v[18:19], v[60:63], off offset:512
	global_store_dwordx4 v[18:19], v[68:71], off offset:1024
	global_store_dwordx4 v[18:19], v[6:9], off offset:1536
	s_waitcnt lgkmcnt(0)
	s_barrier
; __device__ __forceinline__ void store2_wt(void* p, unsigned v) { asm volatile("global_store_short %0, %1, off sc1" :: "v"(p), "v"(v) : "memory"); }
; #define LDS_SYNC() do { asm volatile("s_waitcnt lgkmcnt(0)" ::: "memory"); __builtin_amdgcn_s_barrier(); asm volatile("" ::: "memory"); } while (0)
; __device__ __forceinline__ unsigned f2bf(float f) { unsigned u = __builtin_bit_cast(unsigned, f); return (u + 0x7fffu + ((u >> 16) & 1u)) >> 16; }
; __device__ __forceinline__ void hgrn_sample_unit(int unit, LAS unsigned char* lds, const float* sh, const float* HLF, const bf16* HQ, const bf16* HV, const bf16* HG, bf16* MIX, float* ohs, gu32* rdy4) {
;     ...
;     LDS_SYNC();
;     const int t = tid >> 7, v = tid & 127; float o = 0.f;
; #pragma unroll
;     for (int q = 0; q < 16; ++q) o += OP[(t * 16 + q) * 128 + v];
;     const float ps = wave_sum(o * o);
;     if ((tid & 63) == 0) PS[wid] = ps;
;     LDS_SYNC();
;     const float rstd = rsqrtf((PS[2 * t] + PS[2 * t + 1]) * (1.0f / 128.0f) + EPSF);
;     const size_t row = (size_t)(MP + 4 * b + t);
;     pg8::store2_wt(MIX + row * 1024 + 512 + h * 128 + v, (unsigned)f2bf(o * rstd * bf2f(HG[row * 512 + h * 128 + v])));
;     asm volatile("s_waitcnt vmcnt(0)" ::: "memory");
;     if ((tid & 63) == 0) __hip_atomic_fetch_add(rdy4 + 64 * (64 + (b >> 6)), 1u, RLX_AGENT);
;     LDS_SYNC();
	ds_read2st64_b32 v[2:3], v36 offset1:2
	ds_read2st64_b32 v[4:5], v36 offset0:4 offset1:6
	ds_read2st64_b32 v[6:7], v36 offset0:8 offset1:10
	s_waitcnt lgkmcnt(2)
	v_add_f32_e32 v2, 0, v2
	v_add_f32_e32 v2, v2, v3
	s_waitcnt lgkmcnt(1)
	v_add_f32_e32 v4, v2, v4
	ds_read2st64_b32 v[2:3], v36 offset0:12 offset1:14
	v_add_f32_e32 v4, v4, v5
	s_waitcnt lgkmcnt(1)
	v_add_f32_e32 v6, v4, v6
	ds_read2st64_b32 v[4:5], v36 offset0:16 offset1:18
	v_add_f32_e32 v6, v6, v7
	s_waitcnt lgkmcnt(1)
	v_add_f32_e32 v2, v6, v2
	v_add_f32_e32 v6, v2, v3
	ds_read2st64_b32 v[2:3], v36 offset0:20 offset1:22
	s_waitcnt lgkmcnt(1)
	v_add_f32_e32 v4, v6, v4
	ds_read2st64_b32 v[6:7], v36 offset0:24 offset1:26
	v_add_f32_e32 v8, v4, v5
	ds_read2st64_b32 v[4:5], v36 offset0:28 offset1:30
	s_waitcnt lgkmcnt(2)
	v_add_f32_e32 v2, v8, v2
	v_add_f32_e32 v2, v2, v3
	s_waitcnt lgkmcnt(1)
	v_add_f32_e32 v2, v2, v6
	v_add_f32_e32 v2, v2, v7
	s_waitcnt lgkmcnt(0)
	v_add_f32_e32 v2, v2, v4
	v_add_f32_e32 v2, v2, v5
	v_cndmask_b32_e32 v4, v37, v39, vcc
	v_mul_f32_e32 v3, v2, v2
	v_lshlrev_b32_e32 v4, 2, v4
	ds_bpermute_b32 v3, v4, v3
	v_cmp_lt_i32_e32 vcc, v40, v38
	s_waitcnt lgkmcnt(0)
	v_fmac_f32_e32 v3, v2, v2
	v_cndmask_b32_e32 v4, v37, v40, vcc
	v_lshlrev_b32_e32 v4, 2, v4
	ds_bpermute_b32 v4, v4, v3
	v_cmp_lt_i32_e32 vcc, v41, v38
	s_waitcnt lgkmcnt(0)
	v_add_f32_e32 v3, v3, v4
	v_cndmask_b32_e32 v4, v37, v41, vcc
	v_lshlrev_b32_e32 v4, 2, v4
	ds_bpermute_b32 v4, v4, v3
	v_cmp_lt_i32_e32 vcc, v42, v38
	s_waitcnt lgkmcnt(0)
	v_add_f32_e32 v3, v3, v4
	v_cndmask_b32_e32 v4, v37, v42, vcc
	v_lshlrev_b32_e32 v4, 2, v4
	ds_bpermute_b32 v4, v4, v3
	v_cmp_lt_i32_e32 vcc, v43, v38
	s_waitcnt lgkmcnt(0)
	v_add_f32_e32 v3, v3, v4
	v_cndmask_b32_e32 v4, v37, v43, vcc
	v_lshlrev_b32_e32 v4, 2, v4
	ds_bpermute_b32 v4, v4, v3
	v_cmp_lt_i32_e32 vcc, v44, v38
	s_waitcnt lgkmcnt(0)
	v_add_f32_e32 v3, v3, v4
	v_cndmask_b32_e32 v4, v37, v44, vcc
	v_lshlrev_b32_e32 v4, 2, v4
	ds_bpermute_b32 v4, v4, v3
	s_and_saveexec_b64 s[24:25], s[6:7]
	s_cbranch_execz .LBB0_604
	s_waitcnt lgkmcnt(0)
	v_add_f32_e32 v3, v3, v4
	ds_write_b32 v34, v3 offset:32768
.LBB0_604:
	s_or_b64 exec, exec, s[24:25]
	s_waitcnt lgkmcnt(0)
	v_add_u32_e32 v4, s22, v35
	v_ashrrev_i32_e32 v5, 31, v4
	v_lshlrev_b64 v[6:7], 10, v[4:5]
	s_lshl_b32 s12, s12, 1
	v_lshl_add_u64 v[6:7], s[18:19], 0, v[6:7]
	v_lshl_add_u64 v[6:7], v[6:7], 0, s[12:13]
	s_waitcnt lgkmcnt(0)
	s_barrier
	v_lshl_add_u64 v[6:7], v[6:7], 0, v[24:25]
	ds_read_b64 v[6:7], v45 offset:32768
	v_lshlrev_b64 v[4:5], 11, v[4:5]
	v_lshl_add_u64 v[4:5], s[10:11], 0, v[4:5]
	v_lshl_add_u64 v[4:5], v[4:5], 0, s[12:13]
	v_lshl_add_u64 v[4:5], v[4:5], 0, v[24:25]
	s_waitcnt lgkmcnt(0)
	v_add_f32_e32 v6, v6, v7
	v_fmamk_f32 v6, v6, 0x3c000000, v46
	v_mul_f32_e32 v7, 0x4b800000, v6
	v_cmp_gt_f32_e32 vcc, s2, v6
	v_lshl_add_u64 v[4:5], v[4:5], 0, s[8:9]
	s_waitcnt vmcnt(8)
	v_lshlrev_b32_e32 v3, 16, v252
	v_cndmask_b32_e32 v6, v6, v7, vcc
	v_rsq_f32_e32 v6, v6
	s_nop 0
	v_mul_f32_e32 v7, 0x45800000, v6
	v_cndmask_b32_e32 v6, v6, v7, vcc
	v_mul_f32_e32 v2, v2, v6
	v_mul_f32_e32 v2, v2, v3
	v_bfe_u32 v3, v2, 16, 1
	v_add3_u32 v2, v2, v3, s3
	v_lshrrev_b32_e32 v2, 16, v2
	global_store_short v[4:5], v2, off sc1
	s_waitcnt vmcnt(0)
	s_and_saveexec_b64 s[22:23], s[6:7]
	s_cbranch_execz .LBB0_601
	s_mov_b64 s[24:25], exec
	v_mbcnt_lo_u32_b32 v2, s24, 0
	v_mbcnt_hi_u32_b32 v2, s25, v2
	v_cmp_eq_u32_e32 vcc, 0, v2
	s_and_b64 s[28:29], exec, vcc
	s_mov_b64 exec, s[28:29]
	s_cbranch_execz .LBB0_601
	s_ashr_i32 s12, s26, 2
	s_and_b32 s28, s12, 0xffffffc0
	s_ashr_i32 s29, s28, 31
	s_lshl_b64 s[28:29], s[28:29], 2
	s_add_u32 s28, s10, s28
	s_addc_u32 s29, s11, s29
	s_bcnt1_i32_b64 s12, s[24:25]
	v_mov_b32_e32 v2, s12
	global_atomic_add v47, v2, s[28:29]
	s_branch .LBB0_601
